# v21 = v20 + tail-loop and memory-attention-unit step barriers wait vmcnt only (no lgkmcnt(0))
# baseline (speedup 1.0000x reference)
.LBB0_609:
	ds_read_b64_tr_b16 v[40:41], v168 offset:54272
	ds_read_b64_tr_b16 v[42:43], v168 offset:54784
	s_waitcnt lgkmcnt(6)
	v_mfma_f32_32x32x16_bf16 v[16:31], v[132:135], v[32:35], v[16:31]
	v_exp_f32_e32 v80, v80
	v_exp_f32_e32 v81, v81
	v_exp_f32_e32 v82, v82
	v_exp_f32_e32 v83, v83
	ds_read_b64_tr_b16 v[32:33], v168 offset:51200
	ds_read_b64_tr_b16 v[34:35], v168 offset:51712
	s_waitcnt lgkmcnt(6)
	v_mfma_f32_32x32x16_bf16 v[0:15], v[132:135], v[48:51], v[0:15]
	v_exp_f32_e32 v84, v84
	v_exp_f32_e32 v85, v85
	v_exp_f32_e32 v86, v86
	v_exp_f32_e32 v87, v87
	ds_read_b64_tr_b16 v[44:45], v168 offset:55296
	ds_read_b64_tr_b16 v[46:47], v168 offset:55808
	s_waitcnt lgkmcnt(6)
	v_mfma_f32_32x32x16_bf16 v[16:31], v[128:131], v[36:39], v[16:31]
	v_exp_f32_e32 v88, v88
	v_exp_f32_e32 v89, v89
	v_exp_f32_e32 v90, v90
	v_exp_f32_e32 v91, v91
	ds_read_b64_tr_b16 v[48:49], v168 offset:52224
	ds_read_b64_tr_b16 v[50:51], v168 offset:52736
	s_waitcnt lgkmcnt(6)
	v_mfma_f32_32x32x16_bf16 v[0:15], v[128:131], v[40:43], v[0:15]
	v_exp_f32_e32 v92, v92
	v_exp_f32_e32 v93, v93
	v_exp_f32_e32 v94, v94
	v_exp_f32_e32 v95, v95
	ds_read_b64_tr_b16 v[40:41], v168 offset:56320
	ds_read_b64_tr_b16 v[42:43], v168 offset:56832
	s_waitcnt lgkmcnt(6)
	v_mfma_f32_32x32x16_bf16 v[16:31], v[124:127], v[32:35], v[16:31]
	v_exp_f32_e32 v64, v64
	v_exp_f32_e32 v65, v65
	v_exp_f32_e32 v66, v66
	v_exp_f32_e32 v67, v67
	v_add_u32_e32 v169, s85, v179
	ds_read_b128 v[32:35], v169
	s_waitcnt lgkmcnt(5)
	v_mfma_f32_32x32x16_bf16 v[0:15], v[124:127], v[44:47], v[0:15]
	v_exp_f32_e32 v68, v68
	v_exp_f32_e32 v69, v69
	v_exp_f32_e32 v70, v70
	v_exp_f32_e32 v71, v71
	ds_read_b128 v[36:39], v169 offset:512
	s_waitcnt lgkmcnt(4)
	v_mfma_f32_32x32x16_bf16 v[16:31], v[120:123], v[48:51], v[16:31]
	v_exp_f32_e32 v72, v72
	v_exp_f32_e32 v73, v73
	v_exp_f32_e32 v74, v74
	v_exp_f32_e32 v75, v75
	ds_read_b128 v[136:139], v169 offset:2048
	s_waitcnt lgkmcnt(3)
	v_mfma_f32_32x32x16_bf16 v[0:15], v[120:123], v[40:43], v[0:15]
	v_exp_f32_e32 v76, v76
	v_exp_f32_e32 v77, v77
	v_exp_f32_e32 v78, v78
	v_exp_f32_e32 v79, v79
	s_mov_b64 s[0:1], -1
	s_and_b64 vcc, exec, s[8:9]
	s_cbranch_vccz .LBB0_645
	s_cmp_ge_u32 s87, s80
	s_cbranch_scc0 .LBB0_612
	s_waitcnt vmcnt(0)
	s_barrier
	s_mov_b64 s[0:1], 0
.LBB0_612:
	s_andn2_b64 vcc, exec, s[0:1]
	s_cbranch_vccnz .LBB0_614
	s_waitcnt vmcnt(1)
	s_barrier

.LBB0_635:
	s_waitcnt lgkmcnt(0)
	v_mfma_f32_32x32x16_bf16 v[0:15], v[120:123], v[64:67], v[0:15]
	v_exp_f32_e32 v44, v44
	v_exp_f32_e32 v45, v45
	v_exp_f32_e32 v46, v46
	v_exp_f32_e32 v47, v47
	s_mov_b64 s[0:1], -1
	s_and_b64 vcc, exec, s[48:49]
	s_cbranch_vccz .LBB0_647
	s_and_b64 vcc, exec, s[8:9]
	s_cbranch_vccz .LBB0_638
	s_waitcnt vmcnt(0)
	s_barrier
	s_mov_b64 s[0:1], 0

.LBB0_646:
	s_waitcnt vmcnt(3)
	s_barrier
	s_andn2_b64 vcc, exec, s[60:61]
	s_cbranch_vccz .LBB0_616
	s_branch .LBB0_617

.LBB0_668:
	v_readlane_b32 s94, v246, 53
	s_ashr_i32 s4, s94, 7
	s_ashr_i32 s5, s4, 31
	s_lshl_b64 s[0:1], s[4:5], 22
	v_readlane_b32 s6, v244, 19
	v_readlane_b32 s7, v244, 20
	s_add_u32 s0, s6, s0
	s_addc_u32 s1, s7, s1
	s_lshl_b32 s2, s72, 6
	s_and_b32 s2, s2, 0xc0
	s_lshl_b32 s12, s2, 1
	s_add_u32 s10, s0, s12
	s_addc_u32 s11, s1, 0
	s_lshl_b64 s[0:1], s[4:5], 17
	s_add_u32 s0, s6, s0
	s_addc_u32 s1, s7, s1
	s_add_u32 s13, s0, s12
	s_addc_u32 s14, s1, 0
	s_add_u32 s0, s13, 0x600000
	s_addc_u32 s1, s14, 0
	s_add_u32 s8, s13, 0x640000
	s_addc_u32 s9, s14, 0
	s_lshl_b32 s2, s70, 8
	s_mov_b32 s3, 0
	s_add_i32 s2, s2, s71
	s_lshl_b64 s[6:7], s[2:3], 9
	s_add_u32 s6, s10, s6
	s_addc_u32 s7, s11, s7
	v_readlane_b32 s10, v246, 55
	s_cmp_lg_u32 0, -1
	v_mov_b32_e32 v149, 0
	v_lshl_add_u32 v33, v148, 9, s10
	v_readlane_b32 s10, v246, 56
	v_lshlrev_b32_e32 v148, 9, v170
	s_nop 0
	v_add_lshl_u32 v0, v181, s10, 9
	s_cselect_b32 s10, 0, 0
	v_lshl_add_u32 v96, v182, 1, v0
	s_add_i32 s15, s73, s10
	s_mov_b32 m0, s15
	s_nop 0
	global_load_lds_dwordx4 v33, s[0:1]
	v_lshl_add_u64 v[0:1], s[6:7], 0, v[148:149]
	s_mov_b32 m0, s33
	s_nop 0
	global_load_lds_dwordx4 v96, s[8:9]
	v_lshl_add_u64 v[0:1], v[150:151], 1, v[0:1]
	s_mov_b32 s6, 0xd000000
	s_add_u32 s10, s13, 0x608000
	v_add_co_u32_e32 v2, vcc, s6, v0
	s_addc_u32 s11, s14, 0
	s_add_i32 s16, s15, 0x3000
	s_mov_b32 m0, s16
	s_nop 0
	global_load_lds_dwordx4 v33, s[10:11]
	v_addc_co_u32_e32 v3, vcc, 0, v1, vcc
	global_load_dwordx4 v[136:139], v[2:3], off
	s_mov_b64 s[6:7], 0xd000000
	v_lshl_add_u64 v[0:1], v[0:1], 0, s[6:7]
	global_load_dwordx4 v[132:135], v[0:1], off offset:32
	global_load_dwordx4 v[128:131], v[0:1], off offset:64
	global_load_dwordx4 v[124:127], v[0:1], off offset:96
	s_add_u32 s6, s13, 0x610000
	s_addc_u32 s7, s14, 0
	s_addk_i32 s15, 0x6000
	s_mov_b32 m0, s15
	s_nop 0
	global_load_lds_dwordx4 v33, s[6:7]
	s_waitcnt vmcnt(3)
	s_barrier
	ds_read_b128 v[0:3], v179
	ds_read_b128 v[34:37], v179 offset:2048
	s_mov_b32 s10, 0x41400000
	s_waitcnt vmcnt(3) lgkmcnt(1)
	v_mfma_f32_32x32x16_bf16 v[16:31], v[0:3], v[136:139], 0
	ds_read_b128 v[0:3], v179 offset:512
	s_waitcnt vmcnt(2) lgkmcnt(1)
	v_mfma_f32_32x32x16_bf16 v[16:31], v[34:37], v[132:135], v[16:31]
	ds_read_b128 v[34:37], v179 offset:2560
	s_waitcnt lgkmcnt(1)
	v_mfma_f32_32x32x16_bf16 v[0:15], v[0:3], v[136:139], 0
	s_waitcnt lgkmcnt(0)
	v_mfma_f32_32x32x16_bf16 v[0:15], v[34:37], v[132:135], v[0:15]
	ds_read_b128 v[34:37], v179 offset:4096
	s_waitcnt vmcnt(1) lgkmcnt(0)
	v_mfma_f32_32x32x16_bf16 v[16:31], v[34:37], v[128:131], v[16:31]
	ds_read_b128 v[34:37], v179 offset:4608
	s_waitcnt lgkmcnt(0)
	v_mfma_f32_32x32x16_bf16 v[0:15], v[34:37], v[128:131], v[0:15]
	ds_read_b128 v[34:37], v179 offset:6144
	s_waitcnt vmcnt(0) lgkmcnt(0)
	v_mfma_f32_32x32x16_bf16 v[16:31], v[34:37], v[124:127], v[16:31]
	ds_read_b128 v[34:37], v179 offset:6656
	s_waitcnt lgkmcnt(0)
	v_mfma_f32_32x32x16_bf16 v[0:15], v[34:37], v[124:127], v[0:15]
	s_nop 8
	v_max_f32_e32 v32, v17, v17
	v_max_f32_e32 v34, v16, v16
	v_max_f32_e32 v32, v34, v32
	v_max3_f32 v35, v18, v19, v1
	v_max3_f32 v32, v32, v0, v2
	v_max3_f32 v34, v35, v22, v23
	v_max3_f32 v32, v32, v3, v20
	v_max3_f32 v34, v34, v6, v7
	v_max3_f32 v32, v32, v21, v4
	v_max3_f32 v34, v34, v26, v27
	v_max3_f32 v32, v32, v5, v24
	v_max3_f32 v34, v34, v10, v11
	v_max3_f32 v32, v32, v25, v8
	v_max3_f32 v34, v34, v30, v31
	v_max3_f32 v32, v32, v9, v28
	v_max3_f32 v34, v34, v14, v15
	v_max3_f32 v32, v32, v29, v12
	v_max3_f32 v32, v32, v13, v34
	v_mov_b32_e32 v34, v32
	s_nop 1
	v_permlane32_swap_b32_e32 v32, v34
	v_max_f32_e32 v34, v34, v34
	v_max_f32_e32 v32, v32, v32
	v_max_f32_e32 v32, v32, v34
	v_cmp_gt_f32_e64 vcc, |v32|, s10
	s_cmp_lg_u64 vcc, 0
	s_cselect_b64 s[6:7], -1, 0
	s_cbranch_vccnz .LBB0_1425
.LBB0_669:
	s_add_u32 s14, s0, 0x18000
	s_addc_u32 s15, s1, 0
	s_cmp_lg_u32 0, -1
	s_cselect_b32 s0, 0, 0
	s_add_i32 s0, s0, s73
	s_waitcnt vmcnt(0)
	s_barrier
	s_add_i32 s1, s0, 0x9000
	s_mov_b32 m0, s1
	s_nop 0
	global_load_lds_dwordx4 v33, s[14:15]
	s_add_u32 s14, s8, 0x8000
	s_addc_u32 s15, s9, 0
	s_add_i32 s1, s0, 0xe000
	s_mov_b32 m0, s1
	s_nop 0
	global_load_lds_dwordx4 v96, s[14:15]
	v_exp_f32_e32 v48, v0
	v_exp_f32_e32 v49, v1
	v_exp_f32_e32 v50, v2
	v_exp_f32_e32 v51, v3
	v_exp_f32_e32 v52, v4
	v_exp_f32_e32 v53, v5
	v_exp_f32_e32 v54, v6
	v_exp_f32_e32 v55, v7
	v_exp_f32_e32 v56, v8
	v_exp_f32_e32 v57, v9
	v_exp_f32_e32 v58, v10
	v_exp_f32_e32 v59, v11
	ds_read_b128 v[0:3], v179 offset:14336
	ds_read_b128 v[4:7], v179 offset:12800
	ds_read_b128 v[8:11], v179 offset:12288
	v_exp_f32_e32 v16, v16
	v_exp_f32_e32 v17, v17
	v_exp_f32_e32 v18, v18
	v_exp_f32_e32 v19, v19
	v_exp_f32_e32 v20, v20
	v_exp_f32_e32 v21, v21
	v_exp_f32_e32 v22, v22
	v_exp_f32_e32 v23, v23
	v_exp_f32_e32 v24, v24
	v_exp_f32_e32 v25, v25
	v_exp_f32_e32 v26, v26
	v_exp_f32_e32 v27, v27
	v_exp_f32_e32 v28, v28
	v_exp_f32_e32 v29, v29
	v_exp_f32_e32 v30, v30
	v_exp_f32_e32 v31, v31
	v_exp_f32_e32 v76, v12
	v_exp_f32_e32 v77, v13
	v_exp_f32_e32 v78, v14
	v_exp_f32_e32 v79, v15
	ds_read_b128 v[12:15], v179 offset:14848
	v_add_f32_e32 v32, v16, v17
	s_waitcnt lgkmcnt(1)
	v_mfma_f32_32x32x16_bf16 v[60:75], v[8:11], v[136:139], 0
	v_add_f32_e32 v32, v18, v32
	v_add_f32_e32 v32, v19, v32
	v_cvt_pk_bf16_f32 v112, v16, v17
	v_add_f32_e32 v32, v20, v32
	v_mov_b32_e32 v113, v112
	v_mov_b32_e32 v114, v112
	v_mov_b32_e32 v115, v112
	ds_read_b128 v[8:11], v179 offset:16384
	v_add_f32_e32 v16, v21, v32
	v_mfma_f32_32x32x16_bf16 v[32:47], v[4:7], v[136:139], 0
	v_add_f32_e32 v16, v22, v16
	v_add_f32_e32 v16, v23, v16
	v_cvt_pk_bf16_f32 v113, v18, v19
	ds_read_b128 v[4:7], v179 offset:16896
	v_mfma_f32_32x32x16_bf16 v[60:75], v[0:3], v[132:135], v[60:75]
	v_add_f32_e32 v16, v24, v16
	v_add_f32_e32 v16, v25, v16
	v_add_f32_e32 v16, v26, v16
	v_cvt_pk_bf16_f32 v114, v20, v21
	ds_read_b128 v[0:3], v179 offset:18432
	s_waitcnt lgkmcnt(3)
	v_mfma_f32_32x32x16_bf16 v[32:47], v[12:15], v[132:135], v[32:47]
	v_add_f32_e32 v16, v27, v16
	v_add_f32_e32 v16, v28, v16
	v_add_f32_e32 v16, v29, v16
	v_cvt_pk_bf16_f32 v115, v22, v23
	ds_read_b128 v[12:15], v179 offset:18944
	s_waitcnt lgkmcnt(3)
	v_mfma_f32_32x32x16_bf16 v[60:75], v[8:11], v[128:131], v[60:75]
	v_add_f32_e32 v16, v30, v16
	v_add_f32_e32 v16, v31, v16
	v_cvt_pk_bf16_f32 v116, v24, v25
	v_add_f32_e32 v16, v48, v16
	v_mov_b32_e32 v117, v116
	v_mov_b32_e32 v118, v116
	v_mov_b32_e32 v119, v116
	s_waitcnt lgkmcnt(2)
	v_mfma_f32_32x32x16_bf16 v[32:47], v[4:7], v[128:131], v[32:47]
	v_add_f32_e32 v8, v49, v16
	v_add_f32_e32 v8, v50, v8
	v_add_f32_e32 v8, v51, v8
	v_cvt_pk_bf16_f32 v117, v26, v27
	s_waitcnt lgkmcnt(1)
	v_mfma_f32_32x32x16_bf16 v[60:75], v[0:3], v[124:127], v[60:75]
	v_add_f32_e32 v4, v52, v8
	v_add_f32_e32 v4, v53, v4
	v_add_f32_e32 v4, v54, v4
	v_cvt_pk_bf16_f32 v118, v28, v29
	s_waitcnt lgkmcnt(0)
	v_mfma_f32_32x32x16_bf16 v[32:47], v[12:15], v[124:127], v[32:47]
	v_add_f32_e32 v0, v55, v4
	v_add_f32_e32 v0, v56, v0
	v_add_f32_e32 v0, v57, v0
	v_cvt_pk_bf16_f32 v119, v30, v31
	s_nop 0
	v_add_f32_e32 v0, v58, v0
	v_add_f32_e32 v4, v59, v0
	v_cvt_pk_bf16_f32 v120, v48, v49
	v_cvt_pk_bf16_f32 v121, v50, v51
	ds_read_b64_tr_b16 v[0:1], v180 offset:49152
	ds_read_b64_tr_b16 v[2:3], v180 offset:49664
	v_add_f32_e32 v4, v76, v4
	v_add_f32_e32 v4, v77, v4
	v_cvt_pk_bf16_f32 v122, v52, v53
	v_cvt_pk_bf16_f32 v123, v54, v55
	ds_read_b64_tr_b16 v[16:17], v180 offset:53248
	ds_read_b64_tr_b16 v[18:19], v180 offset:53760
	v_add_f32_e32 v4, v78, v4
	v_cvt_pk_bf16_f32 v108, v56, v57
	v_cvt_pk_bf16_f32 v109, v58, v59
	ds_read_b64_tr_b16 v[48:49], v180 offset:50176
	ds_read_b64_tr_b16 v[50:51], v180 offset:50688
	v_add_f32_e32 v4, v79, v4
	v_cvt_pk_bf16_f32 v110, v76, v77
	v_cvt_pk_bf16_f32 v111, v78, v79
	s_nop 0
	v_add_f32_e32 v97, 0, v4
	v_max_f32_e32 v4, v61, v61
	v_max_f32_e32 v5, v60, v60
	v_max_f32_e32 v4, v5, v4
	v_max3_f32 v5, v62, v63, v33
	v_max3_f32 v4, v4, v32, v34
	v_max3_f32 v4, v4, v35, v64
	v_max3_f32 v5, v5, v66, v67
	v_max3_f32 v4, v4, v65, v36
	v_max3_f32 v5, v5, v38, v39
	v_max3_f32 v4, v4, v37, v68
	v_max3_f32 v5, v5, v70, v71
	v_max3_f32 v4, v4, v69, v40
	v_max3_f32 v5, v5, v42, v43
	v_max3_f32 v4, v4, v41, v72
	v_max3_f32 v5, v5, v74, v75
	v_max3_f32 v4, v4, v73, v44
	v_max3_f32 v5, v5, v46, v47
	v_max3_f32 v4, v4, v45, v5
	v_readlane_b32 s84, v246, 28
	s_add_u32 s14, s8, 0x10000
	v_sub_f32_e32 v5, v4, v149
	v_readlane_b32 s85, v246, 29
	s_addc_u32 s15, s9, 0
	s_add_i32 s0, s0, 0x10000
	s_mov_b32 m0, s0
	s_nop 0
	global_load_lds_dwordx4 v96, s[14:15]
	v_cmp_lt_f32_e32 vcc, s10, v5
	v_readlane_b32 s86, v246, 30
	v_readlane_b32 s87, v246, 31
	v_readlane_b32 s88, v246, 32
	v_readlane_b32 s89, v246, 33
	s_mov_b64 s[80:81], s[84:85]
	s_cmp_lg_u64 vcc, 0
	v_readlane_b32 s91, v246, 35
	s_mov_b64 s[82:83], s[86:87]
	s_mov_b64 s[84:85], s[88:89]
	v_readlane_b32 s60, v246, 19
	v_readlane_b32 s88, v246, 36
	s_cselect_b64 s[10:11], -1, 0
	v_readlane_b32 s64, v246, 23
	v_readlane_b32 s65, v246, 24
	v_readlane_b32 s66, v246, 25
	v_readlane_b32 s67, v246, 26
	v_readlane_b32 s89, v246, 37
	v_readlane_b32 s91, v246, 54
	v_readlane_b32 s90, v246, 34
	v_readlane_b32 s61, v246, 20
	v_readlane_b32 s62, v246, 21
	v_readlane_b32 s63, v246, 22
	s_cbranch_vccnz .LBB0_1426
	v_readlane_b32 s90, v246, 60
	s_mov_b32 s73, s46
	s_andn2_b64 vcc, exec, s[6:7]
	s_cbranch_vccnz .LBB0_672

.LBB0_672:
	ds_read_b64_tr_b16 v[52:53], v180 offset:54272
	ds_read_b64_tr_b16 v[54:55], v180 offset:54784
	s_waitcnt lgkmcnt(6)
	v_mfma_f32_32x32x16_bf16 v[0:15], v[112:115], v[0:3], 0
	v_exp_f32_e32 v60, v60
	v_exp_f32_e32 v61, v61
	v_exp_f32_e32 v62, v62
	v_exp_f32_e32 v63, v63
	ds_read_b64_tr_b16 v[56:57], v180 offset:51200
	ds_read_b64_tr_b16 v[58:59], v180 offset:51712
	s_waitcnt lgkmcnt(6)
	v_mfma_f32_32x32x16_bf16 v[16:31], v[112:115], v[16:19], 0
	v_exp_f32_e32 v64, v64
	v_exp_f32_e32 v65, v65
	v_exp_f32_e32 v66, v66
	v_exp_f32_e32 v67, v67
	ds_read_b64_tr_b16 v[76:77], v180 offset:55296
	ds_read_b64_tr_b16 v[78:79], v180 offset:55808
	s_waitcnt lgkmcnt(6)
	v_mfma_f32_32x32x16_bf16 v[0:15], v[116:119], v[48:51], v[0:15]
	v_exp_f32_e32 v68, v68
	v_exp_f32_e32 v69, v69
	v_exp_f32_e32 v70, v70
	v_exp_f32_e32 v71, v71
	ds_read_b64_tr_b16 v[80:81], v180 offset:52224
	ds_read_b64_tr_b16 v[82:83], v180 offset:52736
	s_waitcnt lgkmcnt(6)
	v_mfma_f32_32x32x16_bf16 v[16:31], v[116:119], v[52:55], v[16:31]
	v_exp_f32_e32 v72, v72
	v_exp_f32_e32 v73, v73
	v_exp_f32_e32 v74, v74
	v_exp_f32_e32 v75, v75
	ds_read_b64_tr_b16 v[84:85], v180 offset:56320
	ds_read_b64_tr_b16 v[86:87], v180 offset:56832
	s_waitcnt lgkmcnt(6)
	v_mfma_f32_32x32x16_bf16 v[0:15], v[120:123], v[56:59], v[0:15]
	v_exp_f32_e32 v32, v32
	v_exp_f32_e32 v33, v33
	v_exp_f32_e32 v34, v34
	v_exp_f32_e32 v35, v35
	ds_read_b128 v[48:51], v179 offset:24576
	s_waitcnt lgkmcnt(5)
	v_mfma_f32_32x32x16_bf16 v[16:31], v[120:123], v[76:79], v[16:31]
	v_exp_f32_e32 v36, v36
	v_exp_f32_e32 v37, v37
	v_exp_f32_e32 v38, v38
	v_exp_f32_e32 v39, v39
	ds_read_b128 v[52:55], v179 offset:25088
	s_waitcnt lgkmcnt(4)
	v_mfma_f32_32x32x16_bf16 v[0:15], v[108:111], v[80:83], v[0:15]
	v_exp_f32_e32 v40, v40
	v_exp_f32_e32 v41, v41
	v_exp_f32_e32 v42, v42
	v_exp_f32_e32 v43, v43
	ds_read_b128 v[92:95], v179 offset:26624
	s_waitcnt lgkmcnt(3)
	v_mfma_f32_32x32x16_bf16 v[16:31], v[108:111], v[84:87], v[16:31]
	v_exp_f32_e32 v44, v44
	v_exp_f32_e32 v45, v45
	v_exp_f32_e32 v46, v46
	v_exp_f32_e32 v47, v47
	s_waitcnt vmcnt(1)
	s_barrier
	s_andn2_b64 vcc, exec, s[10:11]
	v_add_u32_e32 v145, s54, v146
	s_cbranch_vccnz .LBB0_674
	s_waitcnt lgkmcnt(0)
	ds_read_b128 v[56:59], v145 offset:96
	ds_read_b128 v[76:79], v145 offset:64
	ds_read_b128 v[80:83], v145 offset:32
	ds_read_b128 v[84:87], v145
	s_waitcnt lgkmcnt(3)
	v_pk_mul_f32 v[12:13], v[12:13], v[56:57]
	s_waitcnt lgkmcnt(2)
	v_pk_mul_f32 v[8:9], v[8:9], v[76:77]
	s_waitcnt lgkmcnt(1)
	v_pk_mul_f32 v[4:5], v[4:5], v[80:81]
	v_pk_mul_f32 v[14:15], v[14:15], v[58:59]
	v_pk_mul_f32 v[10:11], v[10:11], v[78:79]
	v_pk_mul_f32 v[6:7], v[6:7], v[82:83]
	s_waitcnt lgkmcnt(0)
	v_pk_mul_f32 v[2:3], v[2:3], v[86:87]
	v_pk_mul_f32 v[0:1], v[0:1], v[84:85]
	v_pk_mul_f32 v[28:29], v[28:29], v[56:57]
	v_pk_mul_f32 v[24:25], v[24:25], v[76:77]
	v_pk_mul_f32 v[20:21], v[20:21], v[80:81]
	v_pk_mul_f32 v[30:31], v[30:31], v[58:59]
	v_pk_mul_f32 v[26:27], v[26:27], v[78:79]
	v_pk_mul_f32 v[22:23], v[22:23], v[82:83]
	v_pk_mul_f32 v[18:19], v[18:19], v[86:87]
	v_pk_mul_f32 v[16:17], v[16:17], v[84:85]

.LBB0_677:
	ds_read_b64_tr_b16 v[40:41], v180 offset:62464
	ds_read_b64_tr_b16 v[42:43], v180 offset:62976
	s_waitcnt lgkmcnt(6)
	v_mfma_f32_32x32x16_bf16 v[0:15], v[112:115], v[64:67], v[0:15]
	v_exp_f32_e32 v76, v76
	v_exp_f32_e32 v77, v77
	v_exp_f32_e32 v78, v78
	v_exp_f32_e32 v79, v79
	ds_read_b64_tr_b16 v[44:45], v180 offset:59392
	ds_read_b64_tr_b16 v[46:47], v180 offset:59904
	s_waitcnt lgkmcnt(6)
	v_mfma_f32_32x32x16_bf16 v[16:31], v[112:115], v[36:39], v[16:31]
	v_exp_f32_e32 v80, v80
	v_exp_f32_e32 v81, v81
	v_exp_f32_e32 v82, v82
	v_exp_f32_e32 v83, v83
	ds_read_b64_tr_b16 v[36:37], v180 offset:63488
	ds_read_b64_tr_b16 v[38:39], v180 offset:64000
	s_waitcnt lgkmcnt(6)
	v_mfma_f32_32x32x16_bf16 v[0:15], v[116:119], v[32:35], v[0:15]
	v_exp_f32_e32 v84, v84
	v_exp_f32_e32 v85, v85
	v_exp_f32_e32 v86, v86
	v_exp_f32_e32 v87, v87
	ds_read_b64_tr_b16 v[64:65], v180 offset:60416
	ds_read_b64_tr_b16 v[66:67], v180 offset:60928
	s_waitcnt lgkmcnt(6)
	v_mfma_f32_32x32x16_bf16 v[16:31], v[116:119], v[40:43], v[16:31]
	v_exp_f32_e32 v88, v88
	v_exp_f32_e32 v89, v89
	v_exp_f32_e32 v90, v90
	v_exp_f32_e32 v91, v91
	ds_read_b64_tr_b16 v[40:41], v180 offset:64512
	ds_read_b64_tr_b16 v[42:43], v180 offset:65024
	s_waitcnt lgkmcnt(6)
	v_mfma_f32_32x32x16_bf16 v[0:15], v[120:123], v[44:47], v[0:15]
	v_exp_f32_e32 v48, v48
	v_exp_f32_e32 v49, v49
	v_exp_f32_e32 v50, v50
	v_exp_f32_e32 v51, v51
	ds_read_b128 v[32:35], v179 offset:36864
	s_waitcnt lgkmcnt(5)
	v_mfma_f32_32x32x16_bf16 v[16:31], v[120:123], v[36:39], v[16:31]
	v_exp_f32_e32 v52, v52
	v_exp_f32_e32 v53, v53
	v_exp_f32_e32 v54, v54
	v_exp_f32_e32 v55, v55
	ds_read_b128 v[36:39], v179 offset:37376
	s_waitcnt lgkmcnt(4)
	v_mfma_f32_32x32x16_bf16 v[0:15], v[108:111], v[64:67], v[0:15]
	v_exp_f32_e32 v56, v56
	v_exp_f32_e32 v57, v57
	v_exp_f32_e32 v58, v58
	v_exp_f32_e32 v59, v59
	ds_read_b128 v[64:67], v179 offset:38912
	s_waitcnt lgkmcnt(3)
	v_mfma_f32_32x32x16_bf16 v[16:31], v[108:111], v[40:43], v[16:31]
	v_exp_f32_e32 v60, v60
	v_exp_f32_e32 v61, v61
	v_exp_f32_e32 v62, v62
	v_exp_f32_e32 v63, v63
	s_waitcnt vmcnt(0)
	s_barrier
	s_andn2_b64 vcc, exec, s[8:9]
	s_cbranch_vccnz .LBB0_679
	s_waitcnt lgkmcnt(0)
	ds_read_b128 v[40:43], v145 offset:96
	ds_read_b128 v[44:47], v145 offset:64
	ds_read_b128 v[70:73], v145 offset:32
	ds_read_b128 v[92:95], v145
	s_waitcnt lgkmcnt(3)
	v_pk_mul_f32 v[12:13], v[12:13], v[40:41]
	s_waitcnt lgkmcnt(2)
	v_pk_mul_f32 v[8:9], v[8:9], v[44:45]
	s_waitcnt lgkmcnt(1)
	v_pk_mul_f32 v[4:5], v[4:5], v[70:71]
	v_pk_mul_f32 v[14:15], v[14:15], v[42:43]
	v_pk_mul_f32 v[10:11], v[10:11], v[46:47]
	v_pk_mul_f32 v[6:7], v[6:7], v[72:73]
	s_waitcnt lgkmcnt(0)
	v_pk_mul_f32 v[2:3], v[2:3], v[94:95]
	v_pk_mul_f32 v[0:1], v[0:1], v[92:93]
	v_pk_mul_f32 v[28:29], v[28:29], v[40:41]
	v_pk_mul_f32 v[24:25], v[24:25], v[44:45]
	v_pk_mul_f32 v[20:21], v[20:21], v[70:71]
	v_pk_mul_f32 v[30:31], v[30:31], v[42:43]
	v_pk_mul_f32 v[26:27], v[26:27], v[46:47]
	v_pk_mul_f32 v[22:23], v[22:23], v[72:73]
	v_pk_mul_f32 v[18:19], v[18:19], v[94:95]
	v_pk_mul_f32 v[16:17], v[16:17], v[92:93]

.LBB0_962:
	s_cmp_lt_i32 s84, 7
	s_cselect_b64 s[0:1], -1, 0
	s_cmp_gt_i32 s85, 6
	s_cselect_b64 s[2:3], -1, 0
	s_and_b64 s[0:1], s[0:1], s[2:3]
	s_andn2_b64 vcc, exec, s[0:1]
	s_mul_i32 s70, s90, 0x3c00
	s_cbranch_vccnz .LBB0_1163
	s_ashr_i32 s6, s94, 7
	s_ashr_i32 s7, s6, 31
	s_mov_b64 s[4:5], s[82:83]
	s_lshl_b64 s[0:1], s[6:7], 22
	s_add_u32 s0, s4, s0
	s_addc_u32 s1, s5, s1
	s_lshl_b32 s2, s94, 1
	s_and_b32 s2, s2, 0xc0
	s_lshl_b32 s14, s2, 1
	s_add_u32 s12, s0, s14
	s_addc_u32 s13, s1, 0
	s_lshl_b64 s[0:1], s[6:7], 17
	s_add_u32 s0, s4, s0
	s_addc_u32 s1, s5, s1
	s_add_u32 s15, s0, s14
	s_addc_u32 s17, s1, 0
	s_add_u32 s0, s15, 0x680000
	s_addc_u32 s1, s17, 0
	s_add_u32 s10, s15, 0x6c0000
	s_addc_u32 s11, s17, 0
	s_lshl_b32 s2, s94, 8
	s_and_b32 s2, s2, 0x1f00
	s_lshl_b32 s8, s90, 5
	s_mov_b32 s3, 0
	s_add_i32 s2, s2, s8
	s_lshl_b64 s[8:9], s[2:3], 9
	s_add_u32 s8, s12, s8
	v_mbcnt_lo_u32_b32 v184, -1, 0
	v_mbcnt_hi_u32_b32 v184, -1, v184
	s_addc_u32 s9, s13, s9
	s_lshl_b32 s13, s90, 3
	v_lshlrev_b32_e32 v134, 3, v184
	s_lshl_b32 s12, s90, 4
	s_and_b32 s13, s13, 0x1fffffe0
	v_and_b32_e32 v137, 24, v134
	v_lshl_add_u32 v33, v184, 9, s12
	s_and_b32 s12, s12, 48
	v_lshrrev_b32_e32 v0, 2, v184
	v_or_b32_e32 v1, s13, v137
	s_lshl_b32 s13, s90, 10
	v_and_b32_e32 v135, 31, v184
	v_ashrrev_i32_e32 v136, 5, v184
	v_add_lshl_u32 v0, v0, s12, 9
	s_cmp_lg_u32 0, -1
	v_lshl_add_u32 v95, v1, 1, v0
	s_cselect_b32 s12, 0, 0
	v_lshlrev_b32_e32 v0, 3, v136
	v_lshlrev_b32_e32 v132, 9, v135
	v_mov_b32_e32 v133, 0
	s_add_i32 s12, s12, s13
	s_mov_b32 m0, s12
	s_nop 0
	global_load_lds_dwordx4 v33, s[0:1]
	v_ashrrev_i32_e32 v1, 31, v0
	v_lshl_add_u64 v[2:3], s[8:9], 0, v[132:133]
	s_add_i32 s16, s12, 0xc000
	s_mov_b32 m0, s16
	s_nop 0
	global_load_lds_dwordx4 v95, s[10:11]
	v_lshl_add_u64 v[0:1], v[0:1], 1, v[2:3]
	s_mov_b32 s8, 0xd000000
	s_add_u32 s18, s15, 0x688000
	v_add_co_u32_e32 v2, vcc, s8, v0
	s_addc_u32 s19, s17, 0
	s_add_i32 s20, s12, 0x3000
	s_mov_b32 m0, s20
	s_nop 0
	global_load_lds_dwordx4 v33, s[18:19]
	v_addc_co_u32_e32 v3, vcc, 0, v1, vcc
	global_load_dwordx4 v[124:127], v[2:3], off
	s_mov_b64 s[8:9], 0xd000000
	v_lshl_add_u64 v[0:1], v[0:1], 0, s[8:9]
	global_load_dwordx4 v[120:123], v[0:1], off offset:32
	global_load_dwordx4 v[116:119], v[0:1], off offset:64
	global_load_dwordx4 v[104:107], v[0:1], off offset:96
	s_add_u32 s8, s15, 0x690000
	v_lshlrev_b32_e32 v0, 4, v135
	v_lshl_add_u32 v1, v136, 10, 0
	s_addc_u32 s9, s17, 0
	s_addk_i32 s12, 0x6000
	s_mov_b32 m0, s12
	s_nop 0
	global_load_lds_dwordx4 v33, s[8:9]
	v_add_u32_e32 v139, v1, v0
	s_waitcnt vmcnt(3)
	s_barrier
	ds_read_b128 v[0:3], v139
	ds_read_b128 v[34:37], v139 offset:2048
	s_mov_b32 s12, 0x41400000
	s_waitcnt vmcnt(3) lgkmcnt(1)
	v_mfma_f32_32x32x16_bf16 v[16:31], v[0:3], v[124:127], 0
	ds_read_b128 v[0:3], v139 offset:512
	s_waitcnt vmcnt(2) lgkmcnt(1)
	v_mfma_f32_32x32x16_bf16 v[16:31], v[34:37], v[120:123], v[16:31]
	ds_read_b128 v[34:37], v139 offset:2560
	s_waitcnt lgkmcnt(1)
	v_mfma_f32_32x32x16_bf16 v[0:15], v[0:3], v[124:127], 0
	s_waitcnt lgkmcnt(0)
	v_mfma_f32_32x32x16_bf16 v[0:15], v[34:37], v[120:123], v[0:15]
	ds_read_b128 v[34:37], v139 offset:4096
	s_waitcnt vmcnt(1) lgkmcnt(0)
	v_mfma_f32_32x32x16_bf16 v[16:31], v[34:37], v[116:119], v[16:31]
	ds_read_b128 v[34:37], v139 offset:4608
	s_waitcnt lgkmcnt(0)
	v_mfma_f32_32x32x16_bf16 v[0:15], v[34:37], v[116:119], v[0:15]
	ds_read_b128 v[34:37], v139 offset:6144
	s_waitcnt vmcnt(0) lgkmcnt(0)
	v_mfma_f32_32x32x16_bf16 v[16:31], v[34:37], v[104:107], v[16:31]
	ds_read_b128 v[34:37], v139 offset:6656
	s_waitcnt lgkmcnt(0)
	v_mfma_f32_32x32x16_bf16 v[0:15], v[34:37], v[104:107], v[0:15]
	s_nop 8
	v_max_f32_e32 v32, v17, v17
	v_max_f32_e32 v34, v16, v16
	v_max_f32_e32 v32, v34, v32
	v_max3_f32 v35, v18, v19, v1
	v_max3_f32 v32, v32, v0, v2
	v_max3_f32 v34, v35, v22, v23
	v_max3_f32 v32, v32, v3, v20
	v_max3_f32 v34, v34, v6, v7
	v_max3_f32 v32, v32, v21, v4
	v_max3_f32 v34, v34, v26, v27
	v_max3_f32 v32, v32, v5, v24
	v_max3_f32 v34, v34, v10, v11
	v_max3_f32 v32, v32, v25, v8
	v_max3_f32 v34, v34, v30, v31
	v_max3_f32 v32, v32, v9, v28
	v_max3_f32 v34, v34, v14, v15
	v_max3_f32 v32, v32, v29, v12
	v_max3_f32 v32, v32, v13, v34
	v_mov_b32_e32 v34, v32
	s_nop 1
	v_permlane32_swap_b32_e32 v32, v34
	v_max_f32_e32 v34, v34, v34
	v_max_f32_e32 v32, v32, v32
	v_max_f32_e32 v32, v32, v34
	v_cmp_gt_f32_e64 vcc, |v32|, s12
	s_cmp_lg_u64 vcc, 0
	s_cselect_b64 s[8:9], -1, 0
	s_cbranch_vccnz .LBB0_1435
.LBB0_964:
	s_lshl_b32 s15, s90, 8
	s_add_i32 s15, s15, 0
	s_add_i32 s15, s15, 0x12000
	s_add_u32 s0, s0, 0x18000
	s_addc_u32 s1, s1, 0
	s_cmp_lg_u32 0, -1
	s_cselect_b32 s17, 0, 0
	s_add_i32 s13, s17, s13
	s_waitcnt vmcnt(0)
	s_barrier
	s_add_i32 s17, s13, 0x9000
	s_mov_b32 m0, s17
	s_nop 0
	global_load_lds_dwordx4 v33, s[0:1]
	s_add_u32 s0, s10, 0x8000
	s_addc_u32 s1, s11, 0
	s_add_i32 s17, s13, 0xe000
	s_mov_b32 m0, s17
	s_nop 0
	global_load_lds_dwordx4 v95, s[0:1]
	v_exp_f32_e32 v34, v0
	v_exp_f32_e32 v35, v1
	v_exp_f32_e32 v36, v2
	v_exp_f32_e32 v37, v3
	v_exp_f32_e32 v38, v4
	v_exp_f32_e32 v39, v5
	v_exp_f32_e32 v40, v6
	v_exp_f32_e32 v41, v7
	v_exp_f32_e32 v42, v8
	v_exp_f32_e32 v43, v9
	v_exp_f32_e32 v44, v10
	v_exp_f32_e32 v45, v11
	ds_read_b128 v[0:3], v139 offset:14336
	ds_read_b128 v[4:7], v139 offset:12800
	ds_read_b128 v[8:11], v139 offset:12288
	v_lshlrev_b32_e32 v32, 1, v184
	v_lshlrev_b32_e32 v144, 4, v184
	v_exp_f32_e32 v16, v16
	v_exp_f32_e32 v17, v17
	v_exp_f32_e32 v18, v18
	v_exp_f32_e32 v19, v19
	v_and_b32_e32 v132, 32, v32
	v_and_b32_e32 v32, 0xc0, v144
	v_lshl_or_b32 v138, v136, 8, v32
	v_add_u32_e32 v32, 0, v132
	v_add3_u32 v94, v32, v137, v138
	v_cmp_gt_u32_e64 s[0:1], 32, v184
	v_lshl_add_u32 v141, v135, 2, s15
	v_exp_f32_e32 v20, v20
	v_exp_f32_e32 v21, v21
	v_exp_f32_e32 v22, v22
	v_exp_f32_e32 v23, v23
	v_exp_f32_e32 v24, v24
	v_exp_f32_e32 v25, v25
	v_exp_f32_e32 v26, v26
	v_exp_f32_e32 v27, v27
	v_exp_f32_e32 v28, v28
	v_exp_f32_e32 v29, v29
	v_exp_f32_e32 v30, v30
	v_exp_f32_e32 v31, v31
	v_exp_f32_e32 v46, v12
	v_exp_f32_e32 v47, v13
	v_exp_f32_e32 v64, v14
	v_exp_f32_e32 v65, v15
	ds_read_b128 v[12:15], v139 offset:14848
	v_add_f32_e32 v32, v16, v17
	s_waitcnt lgkmcnt(1)
	v_mfma_f32_32x32x16_bf16 v[78:93], v[8:11], v[124:127], 0
	v_add_f32_e32 v32, v18, v32
	v_add_f32_e32 v32, v19, v32
	v_cvt_pk_bf16_f32 v100, v16, v17
	v_add_f32_e32 v32, v20, v32
	v_mov_b32_e32 v101, v100
	v_mov_b32_e32 v102, v100
	v_mov_b32_e32 v103, v100
	ds_read_b128 v[8:11], v139 offset:16384
	v_mfma_f32_32x32x16_bf16 v[48:63], v[4:7], v[124:127], 0
	v_add_f32_e32 v16, v21, v32
	v_add_f32_e32 v16, v22, v16
	v_add_f32_e32 v16, v23, v16
	v_cvt_pk_bf16_f32 v101, v18, v19
	ds_read_b128 v[4:7], v139 offset:16896
	v_mfma_f32_32x32x16_bf16 v[78:93], v[0:3], v[120:123], v[78:93]
	v_add_f32_e32 v16, v24, v16
	v_add_f32_e32 v16, v25, v16
	v_add_f32_e32 v16, v26, v16
	v_cvt_pk_bf16_f32 v102, v20, v21
	ds_read_b128 v[0:3], v139 offset:18432
	s_waitcnt lgkmcnt(3)
	v_mfma_f32_32x32x16_bf16 v[48:63], v[12:15], v[120:123], v[48:63]
	v_add_f32_e32 v16, v27, v16
	v_add_f32_e32 v16, v28, v16
	v_add_f32_e32 v16, v29, v16
	v_cvt_pk_bf16_f32 v103, v22, v23
	ds_read_b128 v[12:15], v139 offset:18944
	s_waitcnt lgkmcnt(3)
	v_mfma_f32_32x32x16_bf16 v[78:93], v[8:11], v[116:119], v[78:93]
	v_add_f32_e32 v16, v30, v16
	v_add_f32_e32 v16, v31, v16
	v_cvt_pk_bf16_f32 v108, v24, v25
	v_add_f32_e32 v16, v34, v16
	v_mov_b32_e32 v109, v108
	v_mov_b32_e32 v110, v108
	v_mov_b32_e32 v111, v108
	s_waitcnt lgkmcnt(2)
	v_mfma_f32_32x32x16_bf16 v[48:63], v[4:7], v[116:119], v[48:63]
	v_add_f32_e32 v8, v35, v16
	v_add_f32_e32 v8, v36, v8
	v_add_f32_e32 v8, v37, v8
	v_cvt_pk_bf16_f32 v109, v26, v27
	s_waitcnt lgkmcnt(1)
	v_mfma_f32_32x32x16_bf16 v[78:93], v[0:3], v[104:107], v[78:93]
	v_add_f32_e32 v4, v38, v8
	v_add_f32_e32 v4, v39, v4
	v_add_f32_e32 v4, v40, v4
	v_cvt_pk_bf16_f32 v110, v28, v29
	s_waitcnt lgkmcnt(0)
	v_mfma_f32_32x32x16_bf16 v[48:63], v[12:15], v[104:107], v[48:63]
	v_add_f32_e32 v0, v41, v4
	v_add_f32_e32 v0, v42, v0
	v_add_f32_e32 v0, v43, v0
	v_cvt_pk_bf16_f32 v111, v30, v31
	s_nop 0
	v_add_f32_e32 v0, v44, v0
	v_add_f32_e32 v4, v45, v0
	v_cvt_pk_bf16_f32 v112, v34, v35
	v_cvt_pk_bf16_f32 v113, v36, v37
	ds_read_b64_tr_b16 v[0:1], v94 offset:49152
	ds_read_b64_tr_b16 v[2:3], v94 offset:49664
	v_add_f32_e32 v4, v46, v4
	v_add_f32_e32 v4, v47, v4
	v_cvt_pk_bf16_f32 v114, v38, v39
	v_cvt_pk_bf16_f32 v115, v40, v41
	ds_read_b64_tr_b16 v[16:17], v94 offset:53248
	ds_read_b64_tr_b16 v[18:19], v94 offset:53760
	v_add_f32_e32 v4, v64, v4
	v_cvt_pk_bf16_f32 v96, v42, v43
	v_cvt_pk_bf16_f32 v97, v44, v45
	ds_read_b64_tr_b16 v[32:33], v94 offset:50176
	ds_read_b64_tr_b16 v[34:35], v94 offset:50688
	v_add_f32_e32 v4, v65, v4
	v_cvt_pk_bf16_f32 v98, v46, v47
	v_cvt_pk_bf16_f32 v99, v64, v65
	s_nop 0
	v_add_f32_e32 v142, 0, v4
	v_max_f32_e32 v4, v79, v79
	v_max_f32_e32 v5, v78, v78
	v_max_f32_e32 v4, v5, v4
	v_max3_f32 v5, v80, v81, v49
	v_max3_f32 v4, v4, v48, v50
	v_max3_f32 v4, v4, v51, v82
	v_max3_f32 v5, v5, v84, v85
	v_max3_f32 v4, v4, v83, v52
	v_max3_f32 v5, v5, v54, v55
	v_max3_f32 v4, v4, v53, v86
	v_max3_f32 v5, v5, v88, v89
	v_max3_f32 v4, v4, v87, v56
	v_max3_f32 v5, v5, v58, v59
	v_max3_f32 v4, v4, v57, v90
	v_max3_f32 v5, v5, v92, v93
	v_max3_f32 v4, v4, v91, v60
	v_max3_f32 v5, v5, v62, v63
	v_max3_f32 v4, v4, v61, v5
	s_add_u32 s18, s10, 0x10000
	v_sub_f32_e32 v5, v4, v133
	s_addc_u32 s19, s11, 0
	s_add_i32 s13, s13, 0x10000
	s_mov_b32 m0, s13
	s_nop 0
	global_load_lds_dwordx4 v95, s[18:19]
	v_cmp_lt_f32_e32 vcc, s12, v5
	s_cmp_lg_u64 vcc, 0
	s_cselect_b64 s[12:13], -1, 0
	s_cbranch_vccnz .LBB0_1436
	s_andn2_b64 vcc, exec, s[8:9]
	s_cbranch_vccnz .LBB0_967

.LBB0_967:
	v_lshlrev_b32_e32 v72, 4, v136
	ds_read_b64_tr_b16 v[36:37], v94 offset:54272
	ds_read_b64_tr_b16 v[38:39], v94 offset:54784
	s_waitcnt lgkmcnt(6)
	v_mfma_f32_32x32x16_bf16 v[0:15], v[100:103], v[0:3], 0
	v_exp_f32_e32 v78, v78
	v_exp_f32_e32 v79, v79
	v_exp_f32_e32 v80, v80
	v_exp_f32_e32 v81, v81
	ds_read_b64_tr_b16 v[40:41], v94 offset:51200
	ds_read_b64_tr_b16 v[42:43], v94 offset:51712
	s_waitcnt lgkmcnt(6)
	v_mfma_f32_32x32x16_bf16 v[16:31], v[100:103], v[16:19], 0
	v_exp_f32_e32 v82, v82
	v_exp_f32_e32 v83, v83
	v_exp_f32_e32 v84, v84
	v_exp_f32_e32 v85, v85
	ds_read_b64_tr_b16 v[44:45], v94 offset:55296
	ds_read_b64_tr_b16 v[46:47], v94 offset:55808
	s_waitcnt lgkmcnt(6)
	v_mfma_f32_32x32x16_bf16 v[0:15], v[108:111], v[32:35], v[0:15]
	v_exp_f32_e32 v86, v86
	v_exp_f32_e32 v87, v87
	v_exp_f32_e32 v88, v88
	v_exp_f32_e32 v89, v89
	ds_read_b64_tr_b16 v[64:65], v94 offset:52224
	ds_read_b64_tr_b16 v[66:67], v94 offset:52736
	s_waitcnt lgkmcnt(6)
	v_mfma_f32_32x32x16_bf16 v[16:31], v[108:111], v[36:39], v[16:31]
	v_exp_f32_e32 v90, v90
	v_exp_f32_e32 v91, v91
	v_exp_f32_e32 v92, v92
	v_exp_f32_e32 v93, v93
	ds_read_b64_tr_b16 v[68:69], v94 offset:56320
	ds_read_b64_tr_b16 v[70:71], v94 offset:56832
	s_waitcnt lgkmcnt(6)
	v_mfma_f32_32x32x16_bf16 v[0:15], v[112:115], v[40:43], v[0:15]
	v_exp_f32_e32 v48, v48
	v_exp_f32_e32 v49, v49
	v_exp_f32_e32 v50, v50
	v_exp_f32_e32 v51, v51
	ds_read_b128 v[32:35], v139 offset:24576
	s_waitcnt lgkmcnt(5)
	v_mfma_f32_32x32x16_bf16 v[16:31], v[112:115], v[44:47], v[16:31]
	v_exp_f32_e32 v52, v52
	v_exp_f32_e32 v53, v53
	v_exp_f32_e32 v54, v54
	v_exp_f32_e32 v55, v55
	ds_read_b128 v[36:39], v139 offset:25088
	s_waitcnt lgkmcnt(4)
	v_mfma_f32_32x32x16_bf16 v[0:15], v[96:99], v[64:67], v[0:15]
	v_exp_f32_e32 v56, v56
	v_exp_f32_e32 v57, v57
	v_exp_f32_e32 v58, v58
	v_exp_f32_e32 v59, v59
	ds_read_b128 v[128:131], v139 offset:26624
	s_waitcnt lgkmcnt(3)
	v_mfma_f32_32x32x16_bf16 v[16:31], v[96:99], v[68:71], v[16:31]
	v_exp_f32_e32 v60, v60
	v_exp_f32_e32 v61, v61
	v_exp_f32_e32 v62, v62
	v_exp_f32_e32 v63, v63
	s_waitcnt vmcnt(1)
	s_barrier
	s_andn2_b64 vcc, exec, s[12:13]
	v_add_u32_e32 v140, s15, v72
	s_cbranch_vccnz .LBB0_969
	s_waitcnt lgkmcnt(0)
	ds_read_b128 v[40:43], v140 offset:96
	ds_read_b128 v[44:47], v140 offset:64
	ds_read_b128 v[64:67], v140 offset:32
	ds_read_b128 v[68:71], v140
	s_waitcnt lgkmcnt(3)
	v_pk_mul_f32 v[12:13], v[12:13], v[40:41]
	s_waitcnt lgkmcnt(2)
	v_pk_mul_f32 v[8:9], v[8:9], v[44:45]
	s_waitcnt lgkmcnt(1)
	v_pk_mul_f32 v[4:5], v[4:5], v[64:65]
	v_pk_mul_f32 v[14:15], v[14:15], v[42:43]
	v_pk_mul_f32 v[10:11], v[10:11], v[46:47]
	v_pk_mul_f32 v[6:7], v[6:7], v[66:67]
	s_waitcnt lgkmcnt(0)
	v_pk_mul_f32 v[2:3], v[2:3], v[70:71]
	v_pk_mul_f32 v[0:1], v[0:1], v[68:69]
	v_pk_mul_f32 v[28:29], v[28:29], v[40:41]
	v_pk_mul_f32 v[24:25], v[24:25], v[44:45]
	v_pk_mul_f32 v[20:21], v[20:21], v[64:65]
	v_pk_mul_f32 v[30:31], v[30:31], v[42:43]
	v_pk_mul_f32 v[26:27], v[26:27], v[46:47]
	v_pk_mul_f32 v[22:23], v[22:23], v[66:67]
	v_pk_mul_f32 v[18:19], v[18:19], v[70:71]
	v_pk_mul_f32 v[16:17], v[16:17], v[68:69]

.LBB0_972:
	ds_read_b64_tr_b16 v[56:57], v94 offset:62464
	ds_read_b64_tr_b16 v[58:59], v94 offset:62976
	s_waitcnt lgkmcnt(6)
	v_mfma_f32_32x32x16_bf16 v[0:15], v[100:103], v[80:83], v[0:15]
	v_exp_f32_e32 v64, v64
	v_exp_f32_e32 v65, v65
	v_exp_f32_e32 v66, v66
	v_exp_f32_e32 v67, v67
	ds_read_b64_tr_b16 v[60:61], v94 offset:59392
	ds_read_b64_tr_b16 v[62:63], v94 offset:59904
	s_waitcnt lgkmcnt(6)
	v_mfma_f32_32x32x16_bf16 v[16:31], v[100:103], v[52:55], v[16:31]
	v_exp_f32_e32 v68, v68
	v_exp_f32_e32 v69, v69
	v_exp_f32_e32 v70, v70
	v_exp_f32_e32 v71, v71
	ds_read_b64_tr_b16 v[52:53], v94 offset:63488
	ds_read_b64_tr_b16 v[54:55], v94 offset:64000
	s_waitcnt lgkmcnt(6)
	v_mfma_f32_32x32x16_bf16 v[0:15], v[108:111], v[48:51], v[0:15]
	v_exp_f32_e32 v72, v72
	v_exp_f32_e32 v73, v73
	v_exp_f32_e32 v74, v74
	v_exp_f32_e32 v75, v75
	ds_read_b64_tr_b16 v[80:81], v94 offset:60416
	ds_read_b64_tr_b16 v[82:83], v94 offset:60928
	s_waitcnt lgkmcnt(6)
	v_mfma_f32_32x32x16_bf16 v[16:31], v[108:111], v[56:59], v[16:31]
	v_exp_f32_e32 v76, v76
	v_exp_f32_e32 v77, v77
	v_exp_f32_e32 v78, v78
	v_exp_f32_e32 v79, v79
	ds_read_b64_tr_b16 v[56:57], v94 offset:64512
	ds_read_b64_tr_b16 v[58:59], v94 offset:65024
	s_waitcnt lgkmcnt(6)
	v_mfma_f32_32x32x16_bf16 v[0:15], v[112:115], v[60:63], v[0:15]
	v_exp_f32_e32 v32, v32
	v_exp_f32_e32 v33, v33
	v_exp_f32_e32 v34, v34
	v_exp_f32_e32 v35, v35
	ds_read_b128 v[48:51], v139 offset:36864
	s_waitcnt lgkmcnt(5)
	v_mfma_f32_32x32x16_bf16 v[16:31], v[112:115], v[52:55], v[16:31]
	v_exp_f32_e32 v36, v36
	v_exp_f32_e32 v37, v37
	v_exp_f32_e32 v38, v38
	v_exp_f32_e32 v39, v39
	ds_read_b128 v[52:55], v139 offset:37376
	s_waitcnt lgkmcnt(4)
	v_mfma_f32_32x32x16_bf16 v[0:15], v[96:99], v[80:83], v[0:15]
	v_exp_f32_e32 v40, v40
	v_exp_f32_e32 v41, v41
	v_exp_f32_e32 v42, v42
	v_exp_f32_e32 v43, v43
	ds_read_b128 v[128:131], v139 offset:38912
	s_waitcnt lgkmcnt(3)
	v_mfma_f32_32x32x16_bf16 v[16:31], v[96:99], v[56:59], v[16:31]
	v_exp_f32_e32 v44, v44
	v_exp_f32_e32 v45, v45
	v_exp_f32_e32 v46, v46
	v_exp_f32_e32 v47, v47
	s_waitcnt vmcnt(0)
	s_barrier
	s_andn2_b64 vcc, exec, s[10:11]
	s_cbranch_vccnz .LBB0_974
	s_waitcnt lgkmcnt(0)
	ds_read_b128 v[56:59], v140 offset:96
	ds_read_b128 v[60:63], v140 offset:64
	ds_read_b128 v[80:83], v140 offset:32
	ds_read_b128 v[84:87], v140
	s_waitcnt lgkmcnt(3)
	v_pk_mul_f32 v[12:13], v[12:13], v[56:57]
	s_waitcnt lgkmcnt(2)
	v_pk_mul_f32 v[8:9], v[8:9], v[60:61]
	s_waitcnt lgkmcnt(1)
	v_pk_mul_f32 v[4:5], v[4:5], v[80:81]
	v_pk_mul_f32 v[14:15], v[14:15], v[58:59]
	v_pk_mul_f32 v[10:11], v[10:11], v[62:63]
	v_pk_mul_f32 v[6:7], v[6:7], v[82:83]
	s_waitcnt lgkmcnt(0)
	v_pk_mul_f32 v[2:3], v[2:3], v[86:87]
	v_pk_mul_f32 v[0:1], v[0:1], v[84:85]
	v_pk_mul_f32 v[28:29], v[28:29], v[56:57]
	v_pk_mul_f32 v[24:25], v[24:25], v[60:61]
	v_pk_mul_f32 v[20:21], v[20:21], v[80:81]
	v_pk_mul_f32 v[30:31], v[30:31], v[58:59]
	v_pk_mul_f32 v[26:27], v[26:27], v[62:63]
	v_pk_mul_f32 v[22:23], v[22:23], v[82:83]
	v_pk_mul_f32 v[18:19], v[18:19], v[86:87]
	v_pk_mul_f32 v[16:17], v[16:17], v[84:85]
